# work queues of both mixer item phases issue the slow sample-stream items first (M1 attention sample items, M3 sample output items)
# speedup vs baseline: 1.0048x; 1.0048x over previous
; __device__ __forceinline__ int lane_id() { int t; asm volatile("v_mbcnt_lo_u32_b32 %0, -1, 0\n\tv_mbcnt_hi_u32_b32 %0, -1, %0" : "=&v"(t)); return t; }
; __device__ __forceinline__ LaItem la_decode(int li) {
;     LaItem it; it.mx = li / 1088; const int r = li - it.mx * 1088;
;     if (r < 1024) { it.smp = false; it.c = r >> 3; it.h = r & 7; it.s = 0; it.row0 = 64 * it.c; it.C = 64; it.pos0 = 64 * it.c; }
;     else { it.smp = true; it.s = (r - 1024) >> 3; it.h = r & 7; it.c = 0; it.row0 = TP + 16 * it.s; it.C = 16; it.pos0 = 1024; }
;     return it;
; __global__ void __launch_bounds__(512, 2) fwd_megakernel(Params P) {
;     ...
;           while (it < N_LA_ITEMS) {
;               unsigned nx = 0; if (wv == 0 && lane_id() == 0) nx = __hip_atomic_fetch_add(ctr, 1u, __ATOMIC_RELAXED, __HIP_MEMORY_SCOPE_AGENT);
;               la_out_item(P, l, lds, it, wv);
.LBB0_510:
	s_add_i32 s0, s28, 0x400
	s_add_i32 s1, s28, 0x800
	s_cmp_lt_u32 s28, 64
	s_cselect_b32 s0, s0, s1
	s_add_i32 s1, s28, 0xffffff80
	s_cmp_lt_u32 s28, 0x80
	s_cselect_b32 s0, s0, s1
	s_add_i32 s1, s28, 0xffffffc0
	s_cmp_lt_u32 s28, 0x480
	s_cselect_b32 s28, s0, s1
	s_and_b64 vcc, exec, s[86:87]
	v_mov_b32_e32 v84, 0
	s_cbranch_vccnz .LBB0_516
	v_mbcnt_lo_u32_b32 v0, -1, 0
	v_mbcnt_hi_u32_b32 v0, -1, v0
	v_mov_b32_e32 v84, 0
	v_cmp_eq_u32_e32 vcc, 0, v0
	s_and_saveexec_b64 s[0:1], vcc
	s_cbranch_execz .LBB0_515
	s_mov_b64 s[14:15], exec
	v_mbcnt_lo_u32_b32 v0, s14, 0
	v_mbcnt_hi_u32_b32 v0, s15, v0
	v_cmp_eq_u32_e32 vcc, 0, v0
	s_and_saveexec_b64 s[8:9], vcc
	s_cbranch_execz .LBB0_514
	s_bcnt1_i32_b64 s14, s[14:15]
	v_mov_b32_e32 v84, s14
	global_atomic_add v84, v9, v84, s[4:5] sc0
